# GEMM K-loops (8 copies): LDS-DMA addressing switched from 64-bit VGPR adds to SGPR base + 32-bit VGPR offset; removes all vector adds from load segments
# speedup vs baseline: 1.0056x; 1.0056x over previous
.LBB0_432:
	ds_read_b128 v[150:153], v159
	ds_read_b128 v[154:157], v159 offset:1024
	ds_read_b128 v[162:165], v159 offset:2048
	ds_read_b128 v[166:169], v159 offset:3072
	ds_read_b128 v[170:173], v160
	ds_read_b128 v[174:177], v160 offset:1024
	ds_read_b128 v[178:181], v160 offset:2048
	ds_read_b128 v[182:185], v160 offset:3072
	s_add_u32 s42, s40, 0xfff00080
	s_addc_u32 s43, s41, -1
	s_cmp_eq_u32 s74, 60
	s_cselect_b32 s45, s35, s43
	s_cselect_b32 s44, s70, s42
	s_cselect_b32 s43, s31, s73
	s_cselect_b32 s42, s71, s72
	s_add_i32 m0, s55, 0xc000
	ds_read_b128 v[186:189], v161
	ds_read_b128 v[190:193], v161 offset:1024
	ds_read_b128 v[194:197], v161 offset:2048
	ds_read_b128 v[198:201], v161 offset:3072
	ds_read_b128 v[202:205], v161 offset:4096
	ds_read_b128 v[206:209], v161 offset:5120
	ds_read_b128 v[210:213], v161 offset:6144
	ds_read_b128 v[214:217], v161 offset:7168
	global_load_lds_dwordx4 v144, s[40:41]
	s_add_i32 m0, s55, 0xe000
	s_nop 0
	global_load_lds_dwordx4 v142, s[40:41]
	s_waitcnt vmcnt(8)
	s_waitcnt lgkmcnt(0)
	s_barrier
	s_setprio 1
	s_waitcnt lgkmcnt(0)
	v_mfma_f32_16x16x32_bf16 v[92:95], v[150:153], v[186:189], v[92:95]
	v_mfma_f32_16x16x32_bf16 v[88:91], v[162:165], v[186:189], v[88:91]
	v_mfma_f32_16x16x32_bf16 v[84:87], v[150:153], v[194:197], v[84:87]
	v_mfma_f32_16x16x32_bf16 v[80:83], v[162:165], v[194:197], v[80:83]
	v_mfma_f32_16x16x32_bf16 v[76:79], v[150:153], v[202:205], v[76:79]
	v_mfma_f32_16x16x32_bf16 v[68:71], v[162:165], v[202:205], v[68:71]
	v_mfma_f32_16x16x32_bf16 v[60:63], v[150:153], v[210:213], v[60:63]
	v_mfma_f32_16x16x32_bf16 v[56:59], v[162:165], v[210:213], v[56:59]
	v_mfma_f32_16x16x32_bf16 v[92:95], v[154:157], v[190:193], v[92:95]
	v_mfma_f32_16x16x32_bf16 v[88:91], v[166:169], v[190:193], v[88:91]
	v_mfma_f32_16x16x32_bf16 v[84:87], v[154:157], v[198:201], v[84:87]
	v_mfma_f32_16x16x32_bf16 v[80:83], v[166:169], v[198:201], v[80:83]
	v_mfma_f32_16x16x32_bf16 v[76:79], v[154:157], v[206:209], v[76:79]
	v_mfma_f32_16x16x32_bf16 v[68:71], v[166:169], v[206:209], v[68:71]
	v_mfma_f32_16x16x32_bf16 v[60:63], v[154:157], v[214:217], v[60:63]
	v_mfma_f32_16x16x32_bf16 v[56:59], v[166:169], v[214:217], v[56:59]
	s_setprio 0
	s_setprio 1
	v_mfma_f32_16x16x32_bf16 v[124:127], v[170:173], v[186:189], v[124:127]
	v_mfma_f32_16x16x32_bf16 v[120:123], v[178:181], v[186:189], v[120:123]
	v_mfma_f32_16x16x32_bf16 v[116:119], v[170:173], v[194:197], v[116:119]
	v_mfma_f32_16x16x32_bf16 v[112:115], v[178:181], v[194:197], v[112:115]
	v_mfma_f32_16x16x32_bf16 v[108:111], v[170:173], v[202:205], v[108:111]
	v_mfma_f32_16x16x32_bf16 v[104:107], v[178:181], v[202:205], v[104:107]
	v_mfma_f32_16x16x32_bf16 v[100:103], v[170:173], v[210:213], v[100:103]
	v_mfma_f32_16x16x32_bf16 v[96:99], v[178:181], v[210:213], v[96:99]
	v_mfma_f32_16x16x32_bf16 v[124:127], v[174:177], v[190:193], v[124:127]
	v_mfma_f32_16x16x32_bf16 v[120:123], v[182:185], v[190:193], v[120:123]
	v_mfma_f32_16x16x32_bf16 v[116:119], v[174:177], v[198:201], v[116:119]
	v_mfma_f32_16x16x32_bf16 v[112:115], v[182:185], v[198:201], v[112:115]
	v_mfma_f32_16x16x32_bf16 v[108:111], v[174:177], v[206:209], v[108:111]
	v_mfma_f32_16x16x32_bf16 v[104:107], v[182:185], v[206:209], v[104:107]
	v_mfma_f32_16x16x32_bf16 v[100:103], v[174:177], v[214:217], v[100:103]
	v_mfma_f32_16x16x32_bf16 v[96:99], v[182:185], v[214:217], v[96:99]
	s_setprio 0
	s_barrier
	s_add_u32 s98, s42, 0x80
	s_addc_u32 s99, s43, 0
	s_add_u32 s100, s44, 0x80
	s_addc_u32 s101, s45, 0
	s_add_i32 s75, s65, s53
	s_mov_b32 m0, s75
	ds_read_b128 v[186:189], v161 offset:16384
	ds_read_b128 v[190:193], v161 offset:17408
	ds_read_b128 v[194:197], v161 offset:18432
	ds_read_b128 v[198:201], v161 offset:19456
	ds_read_b128 v[202:205], v161 offset:20480
	ds_read_b128 v[206:209], v161 offset:21504
	ds_read_b128 v[210:213], v161 offset:22528
	ds_read_b128 v[214:217], v161 offset:23552
	global_load_lds_dwordx4 v132, s[42:43]
	s_add_i32 m0, s75, 0x2000
	s_add_u32 s76, s42, 0x100000
	s_addc_u32 s77, s43, 0
	s_add_i32 s75, s66, s53
	global_load_lds_dwordx4 v128, s[42:43]
	s_mov_b32 m0, s75
	s_nop 0
	global_load_lds_dwordx4 v132, s[76:77]
	s_add_i32 m0, s75, 0x2000
	s_nop 0
	global_load_lds_dwordx4 v128, s[76:77]
	s_mov_b32 m0, s55
	s_nop 0
	global_load_lds_dwordx4 v134, s[44:45]
	s_mov_b32 m0, s56
	s_nop 0
	global_load_lds_dwordx4 v130, s[44:45]
	s_waitcnt vmcnt(8)
	s_waitcnt lgkmcnt(0)
	s_barrier
	s_setprio 1
	s_waitcnt lgkmcnt(0)
	v_mfma_f32_16x16x32_bf16 v[32:35], v[150:153], v[186:189], v[32:35]
	v_mfma_f32_16x16x32_bf16 v[28:31], v[162:165], v[186:189], v[28:31]
	v_mfma_f32_16x16x32_bf16 v[20:23], v[150:153], v[194:197], v[20:23]
	v_mfma_f32_16x16x32_bf16 v[16:19], v[162:165], v[194:197], v[16:19]
	v_mfma_f32_16x16x32_bf16 v[12:15], v[150:153], v[202:205], v[12:15]
	v_mfma_f32_16x16x32_bf16 v[8:11], v[162:165], v[202:205], v[8:11]
	v_mfma_f32_16x16x32_bf16 v[4:7], v[150:153], v[210:213], v[4:7]
	v_mfma_f32_16x16x32_bf16 v[0:3], v[162:165], v[210:213], v[0:3]
	v_mfma_f32_16x16x32_bf16 v[32:35], v[154:157], v[190:193], v[32:35]
	v_mfma_f32_16x16x32_bf16 v[28:31], v[166:169], v[190:193], v[28:31]
	v_mfma_f32_16x16x32_bf16 v[20:23], v[154:157], v[198:201], v[20:23]
	v_mfma_f32_16x16x32_bf16 v[16:19], v[166:169], v[198:201], v[16:19]
	v_mfma_f32_16x16x32_bf16 v[12:15], v[154:157], v[206:209], v[12:15]
	v_mfma_f32_16x16x32_bf16 v[8:11], v[166:169], v[206:209], v[8:11]
	v_mfma_f32_16x16x32_bf16 v[4:7], v[154:157], v[214:217], v[4:7]
	v_mfma_f32_16x16x32_bf16 v[0:3], v[166:169], v[214:217], v[0:3]
	s_setprio 0
	s_setprio 1
	v_mfma_f32_16x16x32_bf16 v[72:75], v[170:173], v[186:189], v[72:75]
	v_mfma_f32_16x16x32_bf16 v[64:67], v[178:181], v[186:189], v[64:67]
	v_mfma_f32_16x16x32_bf16 v[52:55], v[170:173], v[194:197], v[52:55]
	v_mfma_f32_16x16x32_bf16 v[48:51], v[178:181], v[194:197], v[48:51]
	v_mfma_f32_16x16x32_bf16 v[44:47], v[170:173], v[202:205], v[44:47]
	v_mfma_f32_16x16x32_bf16 v[40:43], v[178:181], v[202:205], v[40:43]
	v_mfma_f32_16x16x32_bf16 v[36:39], v[170:173], v[210:213], v[36:39]
	v_mfma_f32_16x16x32_bf16 v[24:27], v[178:181], v[210:213], v[24:27]
	v_mfma_f32_16x16x32_bf16 v[72:75], v[174:177], v[190:193], v[72:75]
	v_mfma_f32_16x16x32_bf16 v[64:67], v[182:185], v[190:193], v[64:67]
	v_mfma_f32_16x16x32_bf16 v[52:55], v[174:177], v[198:201], v[52:55]
	v_mfma_f32_16x16x32_bf16 v[48:51], v[182:185], v[198:201], v[48:51]
	v_mfma_f32_16x16x32_bf16 v[44:47], v[174:177], v[206:209], v[44:47]
	v_mfma_f32_16x16x32_bf16 v[40:43], v[182:185], v[206:209], v[40:43]
	v_mfma_f32_16x16x32_bf16 v[36:39], v[174:177], v[214:217], v[36:39]
	v_mfma_f32_16x16x32_bf16 v[24:27], v[182:185], v[214:217], v[24:27]
	s_setprio 0
	s_barrier
	s_add_i32 s75, 0, 0x18000
	v_add_u32_e32 v136, s75, v158
	s_add_i32 s76, 0, 0x1c000
	ds_read_b128 v[150:153], v136
	ds_read_b128 v[154:157], v136 offset:1024
	ds_read_b128 v[162:165], v136 offset:2048
	ds_read_b128 v[166:169], v136 offset:3072
	v_add_u32_e32 v136, s76, v158
	ds_read_b128 v[170:173], v136
	ds_read_b128 v[174:177], v136 offset:1024
	ds_read_b128 v[178:181], v136 offset:2048
	ds_read_b128 v[182:185], v136 offset:3072
	s_add_u32 s44, s44, 0x100000
	s_addc_u32 s45, s45, 0
	s_mov_b32 m0, s57
	ds_read_b128 v[186:189], v161 offset:32768
	ds_read_b128 v[190:193], v161 offset:33792
	ds_read_b128 v[194:197], v161 offset:34816
	ds_read_b128 v[198:201], v161 offset:35840
	ds_read_b128 v[202:205], v161 offset:36864
	ds_read_b128 v[206:209], v161 offset:37888
	ds_read_b128 v[210:213], v161 offset:38912
	ds_read_b128 v[214:217], v161 offset:39936
	global_load_lds_dwordx4 v134, s[44:45]
	s_mov_b32 m0, s58
	s_nop 0
	global_load_lds_dwordx4 v130, s[44:45]
	s_waitcnt vmcnt(8)
	s_waitcnt lgkmcnt(0)
	s_barrier
	s_setprio 1
	s_waitcnt lgkmcnt(0)
	v_mfma_f32_16x16x32_bf16 v[92:95], v[150:153], v[186:189], v[92:95]
	v_mfma_f32_16x16x32_bf16 v[88:91], v[162:165], v[186:189], v[88:91]
	v_mfma_f32_16x16x32_bf16 v[84:87], v[150:153], v[194:197], v[84:87]
	v_mfma_f32_16x16x32_bf16 v[80:83], v[162:165], v[194:197], v[80:83]
	v_mfma_f32_16x16x32_bf16 v[76:79], v[150:153], v[202:205], v[76:79]
	v_mfma_f32_16x16x32_bf16 v[68:71], v[162:165], v[202:205], v[68:71]
	v_mfma_f32_16x16x32_bf16 v[60:63], v[150:153], v[210:213], v[60:63]
	v_mfma_f32_16x16x32_bf16 v[56:59], v[162:165], v[210:213], v[56:59]
	v_mfma_f32_16x16x32_bf16 v[92:95], v[154:157], v[190:193], v[92:95]
	v_mfma_f32_16x16x32_bf16 v[88:91], v[166:169], v[190:193], v[88:91]
	v_mfma_f32_16x16x32_bf16 v[84:87], v[154:157], v[198:201], v[84:87]
	v_mfma_f32_16x16x32_bf16 v[80:83], v[166:169], v[198:201], v[80:83]
	v_mfma_f32_16x16x32_bf16 v[76:79], v[154:157], v[206:209], v[76:79]
	v_mfma_f32_16x16x32_bf16 v[68:71], v[166:169], v[206:209], v[68:71]
	v_mfma_f32_16x16x32_bf16 v[60:63], v[154:157], v[214:217], v[60:63]
	v_mfma_f32_16x16x32_bf16 v[56:59], v[166:169], v[214:217], v[56:59]
	s_setprio 0
	s_setprio 1
	v_mfma_f32_16x16x32_bf16 v[124:127], v[170:173], v[186:189], v[124:127]
	v_mfma_f32_16x16x32_bf16 v[120:123], v[178:181], v[186:189], v[120:123]
	v_mfma_f32_16x16x32_bf16 v[116:119], v[170:173], v[194:197], v[116:119]
	v_mfma_f32_16x16x32_bf16 v[112:115], v[178:181], v[194:197], v[112:115]
	v_mfma_f32_16x16x32_bf16 v[108:111], v[170:173], v[202:205], v[108:111]
	v_mfma_f32_16x16x32_bf16 v[104:107], v[178:181], v[202:205], v[104:107]
	v_mfma_f32_16x16x32_bf16 v[100:103], v[170:173], v[210:213], v[100:103]
	v_mfma_f32_16x16x32_bf16 v[96:99], v[178:181], v[210:213], v[96:99]
	v_mfma_f32_16x16x32_bf16 v[124:127], v[174:177], v[190:193], v[124:127]
	v_mfma_f32_16x16x32_bf16 v[120:123], v[182:185], v[190:193], v[120:123]
	v_mfma_f32_16x16x32_bf16 v[116:119], v[174:177], v[198:201], v[116:119]
	v_mfma_f32_16x16x32_bf16 v[112:115], v[182:185], v[198:201], v[112:115]
	v_mfma_f32_16x16x32_bf16 v[108:111], v[174:177], v[206:209], v[108:111]
	v_mfma_f32_16x16x32_bf16 v[104:107], v[182:185], v[206:209], v[104:107]
	v_mfma_f32_16x16x32_bf16 v[100:103], v[174:177], v[214:217], v[100:103]
	v_mfma_f32_16x16x32_bf16 v[96:99], v[182:185], v[214:217], v[96:99]
	s_setprio 0
	s_barrier
	s_add_i32 s44, s75, s53
	s_mov_b32 m0, s44
	ds_read_b128 v[186:189], v161 offset:49152
	ds_read_b128 v[190:193], v161 offset:50176
	ds_read_b128 v[194:197], v161 offset:51200
	ds_read_b128 v[198:201], v161 offset:52224
	ds_read_b128 v[202:205], v161 offset:53248
	ds_read_b128 v[206:209], v161 offset:54272
	ds_read_b128 v[210:213], v161 offset:55296
	ds_read_b128 v[214:217], v161 offset:56320
	global_load_lds_dwordx4 v132, s[98:99]
	s_add_i32 m0, s44, 0x2000
	s_add_u32 s42, s42, 0x100080
	s_addc_u32 s43, s43, 0
	s_add_i32 s44, s76, s53
	global_load_lds_dwordx4 v128, s[98:99]
	s_mov_b32 m0, s44
	s_nop 0
	global_load_lds_dwordx4 v132, s[42:43]
	s_add_i32 m0, s44, 0x2000
	s_nop 0
	global_load_lds_dwordx4 v128, s[42:43]
	s_mov_b32 m0, s62
	s_nop 0
	global_load_lds_dwordx4 v134, s[100:101]
	s_mov_b32 m0, s63
	s_nop 0
	global_load_lds_dwordx4 v130, s[100:101]
	s_waitcnt vmcnt(8)
	s_waitcnt lgkmcnt(0)
	s_barrier
	s_setprio 1
	s_waitcnt lgkmcnt(0)
	v_mfma_f32_16x16x32_bf16 v[32:35], v[150:153], v[186:189], v[32:35]
	v_mfma_f32_16x16x32_bf16 v[28:31], v[162:165], v[186:189], v[28:31]
	v_mfma_f32_16x16x32_bf16 v[20:23], v[150:153], v[194:197], v[20:23]
	v_mfma_f32_16x16x32_bf16 v[16:19], v[162:165], v[194:197], v[16:19]
	v_mfma_f32_16x16x32_bf16 v[12:15], v[150:153], v[202:205], v[12:15]
	v_mfma_f32_16x16x32_bf16 v[8:11], v[162:165], v[202:205], v[8:11]
	v_mfma_f32_16x16x32_bf16 v[4:7], v[150:153], v[210:213], v[4:7]
	v_mfma_f32_16x16x32_bf16 v[0:3], v[162:165], v[210:213], v[0:3]
	v_mfma_f32_16x16x32_bf16 v[32:35], v[154:157], v[190:193], v[32:35]
	v_mfma_f32_16x16x32_bf16 v[28:31], v[166:169], v[190:193], v[28:31]
	v_mfma_f32_16x16x32_bf16 v[20:23], v[154:157], v[198:201], v[20:23]
	v_mfma_f32_16x16x32_bf16 v[16:19], v[166:169], v[198:201], v[16:19]
	v_mfma_f32_16x16x32_bf16 v[12:15], v[154:157], v[206:209], v[12:15]
	v_mfma_f32_16x16x32_bf16 v[8:11], v[166:169], v[206:209], v[8:11]
	v_mfma_f32_16x16x32_bf16 v[4:7], v[154:157], v[214:217], v[4:7]
	v_mfma_f32_16x16x32_bf16 v[0:3], v[166:169], v[214:217], v[0:3]
	s_setprio 0
	s_setprio 1
	v_mfma_f32_16x16x32_bf16 v[72:75], v[170:173], v[186:189], v[72:75]
	v_mfma_f32_16x16x32_bf16 v[64:67], v[178:181], v[186:189], v[64:67]
	v_mfma_f32_16x16x32_bf16 v[52:55], v[170:173], v[194:197], v[52:55]
	v_mfma_f32_16x16x32_bf16 v[48:51], v[178:181], v[194:197], v[48:51]
	v_mfma_f32_16x16x32_bf16 v[44:47], v[170:173], v[202:205], v[44:47]
	v_mfma_f32_16x16x32_bf16 v[40:43], v[178:181], v[202:205], v[40:43]
	v_mfma_f32_16x16x32_bf16 v[36:39], v[170:173], v[210:213], v[36:39]
	v_mfma_f32_16x16x32_bf16 v[24:27], v[178:181], v[210:213], v[24:27]
	v_mfma_f32_16x16x32_bf16 v[72:75], v[174:177], v[190:193], v[72:75]
	v_mfma_f32_16x16x32_bf16 v[64:67], v[182:185], v[190:193], v[64:67]
	v_mfma_f32_16x16x32_bf16 v[52:55], v[174:177], v[198:201], v[52:55]
	v_mfma_f32_16x16x32_bf16 v[48:51], v[182:185], v[198:201], v[48:51]
	v_mfma_f32_16x16x32_bf16 v[44:47], v[174:177], v[206:209], v[44:47]
	v_mfma_f32_16x16x32_bf16 v[40:43], v[182:185], v[206:209], v[40:43]
	v_mfma_f32_16x16x32_bf16 v[36:39], v[174:177], v[214:217], v[36:39]
	v_mfma_f32_16x16x32_bf16 v[24:27], v[182:185], v[214:217], v[24:27]
	s_setprio 0
	s_barrier
	s_add_i32 s74, s74, 2
	s_add_u32 s72, s72, 0x100
	s_addc_u32 s73, s73, 0
	s_add_u32 s40, s40, 0x100
	s_addc_u32 s41, s41, 0
	s_cmp_gt_u32 s74, 61
	s_cbranch_scc0 .LBB0_432
	s_and_b64 vcc, exec, s[14:15]
	s_cbranch_vccz .LBB0_436
	s_barrier
	v_lshl_add_u32 v150, s12, 8, v139
	s_cmp_lg_u32 s69, 54
	s_mov_b64 s[40:41], -1
	s_cbranch_scc1 .LBB0_437

.LBB0_1612:
	ds_read_b128 v[144:147], v151
	ds_read_b128 v[156:159], v151 offset:1024
	ds_read_b128 v[160:163], v151 offset:2048
	ds_read_b128 v[164:167], v151 offset:3072
	ds_read_b128 v[168:171], v152
	ds_read_b128 v[172:175], v152 offset:1024
	ds_read_b128 v[176:179], v152 offset:2048
	ds_read_b128 v[180:183], v152 offset:3072
	s_add_u32 s34, s30, 0xfff00080
	s_addc_u32 s35, s31, -1
	s_cmp_eq_u32 s59, 60
	s_cselect_b32 s37, s25, s35
	s_cselect_b32 s36, s55, s34
	s_cselect_b32 s35, s23, s58
	s_cselect_b32 s34, s56, s57
	s_add_i32 m0, s9, 0xc000
	ds_read_b128 v[184:187], v153
	ds_read_b128 v[188:191], v153 offset:1024
	ds_read_b128 v[192:195], v153 offset:2048
	ds_read_b128 v[196:199], v153 offset:3072
	ds_read_b128 v[200:203], v153 offset:4096
	ds_read_b128 v[204:207], v153 offset:5120
	ds_read_b128 v[208:211], v153 offset:6144
	ds_read_b128 v[212:215], v153 offset:7168
	global_load_lds_dwordx4 v138, s[30:31]
	s_add_i32 m0, s9, 0xe000
	s_nop 0
	global_load_lds_dwordx4 v136, s[30:31]
	s_waitcnt vmcnt(8)
	s_waitcnt lgkmcnt(0)
	s_barrier
	s_setprio 1
	s_waitcnt lgkmcnt(0)
	v_mfma_f32_16x16x32_bf16 v[124:127], v[144:147], v[184:187], v[124:127]
	v_mfma_f32_16x16x32_bf16 v[120:123], v[160:163], v[184:187], v[120:123]
	v_mfma_f32_16x16x32_bf16 v[108:111], v[144:147], v[192:195], v[108:111]
	v_mfma_f32_16x16x32_bf16 v[104:107], v[160:163], v[192:195], v[104:107]
	v_mfma_f32_16x16x32_bf16 v[92:95], v[144:147], v[200:203], v[92:95]
	v_mfma_f32_16x16x32_bf16 v[88:91], v[160:163], v[200:203], v[88:91]
	v_mfma_f32_16x16x32_bf16 v[76:79], v[144:147], v[208:211], v[76:79]
	v_mfma_f32_16x16x32_bf16 v[72:75], v[160:163], v[208:211], v[72:75]
	v_mfma_f32_16x16x32_bf16 v[124:127], v[156:159], v[188:191], v[124:127]
	v_mfma_f32_16x16x32_bf16 v[120:123], v[164:167], v[188:191], v[120:123]
	v_mfma_f32_16x16x32_bf16 v[108:111], v[156:159], v[196:199], v[108:111]
	v_mfma_f32_16x16x32_bf16 v[104:107], v[164:167], v[196:199], v[104:107]
	v_mfma_f32_16x16x32_bf16 v[92:95], v[156:159], v[204:207], v[92:95]
	v_mfma_f32_16x16x32_bf16 v[88:91], v[164:167], v[204:207], v[88:91]
	v_mfma_f32_16x16x32_bf16 v[76:79], v[156:159], v[212:215], v[76:79]
	v_mfma_f32_16x16x32_bf16 v[72:75], v[164:167], v[212:215], v[72:75]
	s_setprio 0
	s_setprio 1
	v_mfma_f32_16x16x32_bf16 v[116:119], v[168:171], v[184:187], v[116:119]
	v_mfma_f32_16x16x32_bf16 v[112:115], v[176:179], v[184:187], v[112:115]
	v_mfma_f32_16x16x32_bf16 v[100:103], v[168:171], v[192:195], v[100:103]
	v_mfma_f32_16x16x32_bf16 v[96:99], v[176:179], v[192:195], v[96:99]
	v_mfma_f32_16x16x32_bf16 v[84:87], v[168:171], v[200:203], v[84:87]
	v_mfma_f32_16x16x32_bf16 v[80:83], v[176:179], v[200:203], v[80:83]
	v_mfma_f32_16x16x32_bf16 v[68:71], v[168:171], v[208:211], v[68:71]
	v_mfma_f32_16x16x32_bf16 v[64:67], v[176:179], v[208:211], v[64:67]
	v_mfma_f32_16x16x32_bf16 v[116:119], v[172:175], v[188:191], v[116:119]
	v_mfma_f32_16x16x32_bf16 v[112:115], v[180:183], v[188:191], v[112:115]
	v_mfma_f32_16x16x32_bf16 v[100:103], v[172:175], v[196:199], v[100:103]
	v_mfma_f32_16x16x32_bf16 v[96:99], v[180:183], v[196:199], v[96:99]
	v_mfma_f32_16x16x32_bf16 v[84:87], v[172:175], v[204:207], v[84:87]
	v_mfma_f32_16x16x32_bf16 v[80:83], v[180:183], v[204:207], v[80:83]
	v_mfma_f32_16x16x32_bf16 v[68:71], v[172:175], v[212:215], v[68:71]
	v_mfma_f32_16x16x32_bf16 v[64:67], v[180:183], v[212:215], v[64:67]
	s_setprio 0
	s_barrier
	s_add_u32 s98, s34, 0x80
	s_addc_u32 s99, s35, 0
	s_add_u32 s100, s36, 0x80
	s_addc_u32 s101, s37, 0
	s_add_i32 s60, s52, s45
	s_mov_b32 m0, s60
	ds_read_b128 v[184:187], v153 offset:16384
	ds_read_b128 v[188:191], v153 offset:17408
	ds_read_b128 v[192:195], v153 offset:18432
	ds_read_b128 v[196:199], v153 offset:19456
	ds_read_b128 v[200:203], v153 offset:20480
	ds_read_b128 v[204:207], v153 offset:21504
	ds_read_b128 v[208:211], v153 offset:22528
	ds_read_b128 v[212:215], v153 offset:23552
	global_load_lds_dwordx4 v130, s[34:35]
	s_add_i32 m0, s60, 0x2000
	s_add_u32 s60, s34, 0x100000
	s_addc_u32 s61, s35, 0
	s_add_i32 s62, s53, s45
	global_load_lds_dwordx4 v134, s[34:35]
	s_mov_b32 m0, s62
	s_nop 0
	global_load_lds_dwordx4 v130, s[60:61]
	s_add_i32 m0, s62, 0x2000
	s_nop 0
	global_load_lds_dwordx4 v134, s[60:61]
	s_mov_b32 m0, s9
	s_nop 0
	global_load_lds_dwordx4 v128, s[36:37]
	s_mov_b32 m0, s46
	s_nop 0
	global_load_lds_dwordx4 v132, s[36:37]
	s_waitcnt vmcnt(8)
	s_waitcnt lgkmcnt(0)
	s_barrier
	s_setprio 1
	s_waitcnt lgkmcnt(0)
	v_mfma_f32_16x16x32_bf16 v[60:63], v[144:147], v[184:187], v[60:63]
	v_mfma_f32_16x16x32_bf16 v[56:59], v[160:163], v[184:187], v[56:59]
	v_mfma_f32_16x16x32_bf16 v[44:47], v[144:147], v[192:195], v[44:47]
	v_mfma_f32_16x16x32_bf16 v[40:43], v[160:163], v[192:195], v[40:43]
	v_mfma_f32_16x16x32_bf16 v[28:31], v[144:147], v[200:203], v[28:31]
	v_mfma_f32_16x16x32_bf16 v[24:27], v[160:163], v[200:203], v[24:27]
	v_mfma_f32_16x16x32_bf16 v[12:15], v[144:147], v[208:211], v[12:15]
	v_mfma_f32_16x16x32_bf16 v[8:11], v[160:163], v[208:211], v[8:11]
	v_mfma_f32_16x16x32_bf16 v[60:63], v[156:159], v[188:191], v[60:63]
	v_mfma_f32_16x16x32_bf16 v[56:59], v[164:167], v[188:191], v[56:59]
	v_mfma_f32_16x16x32_bf16 v[44:47], v[156:159], v[196:199], v[44:47]
	v_mfma_f32_16x16x32_bf16 v[40:43], v[164:167], v[196:199], v[40:43]
	v_mfma_f32_16x16x32_bf16 v[28:31], v[156:159], v[204:207], v[28:31]
	v_mfma_f32_16x16x32_bf16 v[24:27], v[164:167], v[204:207], v[24:27]
	v_mfma_f32_16x16x32_bf16 v[12:15], v[156:159], v[212:215], v[12:15]
	v_mfma_f32_16x16x32_bf16 v[8:11], v[164:167], v[212:215], v[8:11]
	s_setprio 0
	s_setprio 1
	v_mfma_f32_16x16x32_bf16 v[52:55], v[168:171], v[184:187], v[52:55]
	v_mfma_f32_16x16x32_bf16 v[48:51], v[176:179], v[184:187], v[48:51]
	v_mfma_f32_16x16x32_bf16 v[36:39], v[168:171], v[192:195], v[36:39]
	v_mfma_f32_16x16x32_bf16 v[32:35], v[176:179], v[192:195], v[32:35]
	v_mfma_f32_16x16x32_bf16 v[20:23], v[168:171], v[200:203], v[20:23]
	v_mfma_f32_16x16x32_bf16 v[16:19], v[176:179], v[200:203], v[16:19]
	v_mfma_f32_16x16x32_bf16 v[4:7], v[168:171], v[208:211], v[4:7]
	v_mfma_f32_16x16x32_bf16 v[0:3], v[176:179], v[208:211], v[0:3]
	v_mfma_f32_16x16x32_bf16 v[52:55], v[172:175], v[188:191], v[52:55]
	v_mfma_f32_16x16x32_bf16 v[48:51], v[180:183], v[188:191], v[48:51]
	v_mfma_f32_16x16x32_bf16 v[36:39], v[172:175], v[196:199], v[36:39]
	v_mfma_f32_16x16x32_bf16 v[32:35], v[180:183], v[196:199], v[32:35]
	v_mfma_f32_16x16x32_bf16 v[20:23], v[172:175], v[204:207], v[20:23]
	v_mfma_f32_16x16x32_bf16 v[16:19], v[180:183], v[204:207], v[16:19]
	v_mfma_f32_16x16x32_bf16 v[4:7], v[172:175], v[212:215], v[4:7]
	v_mfma_f32_16x16x32_bf16 v[0:3], v[180:183], v[212:215], v[0:3]
	s_setprio 0
	s_barrier
	s_add_i32 s60, 0, 0x18000
	v_add_u32_e32 v155, s60, v149
	s_add_i32 s61, 0, 0x1c000
	ds_read_b128 v[144:147], v155
	ds_read_b128 v[156:159], v155 offset:1024
	ds_read_b128 v[160:163], v155 offset:2048
	ds_read_b128 v[164:167], v155 offset:3072
	v_add_u32_e32 v155, s61, v149
	ds_read_b128 v[168:171], v155
	ds_read_b128 v[172:175], v155 offset:1024
	ds_read_b128 v[176:179], v155 offset:2048
	ds_read_b128 v[180:183], v155 offset:3072
	s_add_u32 s36, s36, 0x100000
	s_addc_u32 s37, s37, 0
	s_mov_b32 m0, s47
	ds_read_b128 v[184:187], v153 offset:32768
	ds_read_b128 v[188:191], v153 offset:33792
	ds_read_b128 v[192:195], v153 offset:34816
	ds_read_b128 v[196:199], v153 offset:35840
	ds_read_b128 v[200:203], v153 offset:36864
	ds_read_b128 v[204:207], v153 offset:37888
	ds_read_b128 v[208:211], v153 offset:38912
	ds_read_b128 v[212:215], v153 offset:39936
	global_load_lds_dwordx4 v128, s[36:37]
	s_mov_b32 m0, s48
	s_nop 0
	global_load_lds_dwordx4 v132, s[36:37]
	s_waitcnt vmcnt(8)
	s_waitcnt lgkmcnt(0)
	s_barrier
	s_setprio 1
	s_waitcnt lgkmcnt(0)
	v_mfma_f32_16x16x32_bf16 v[124:127], v[144:147], v[184:187], v[124:127]
	v_mfma_f32_16x16x32_bf16 v[120:123], v[160:163], v[184:187], v[120:123]
	v_mfma_f32_16x16x32_bf16 v[108:111], v[144:147], v[192:195], v[108:111]
	v_mfma_f32_16x16x32_bf16 v[104:107], v[160:163], v[192:195], v[104:107]
	v_mfma_f32_16x16x32_bf16 v[92:95], v[144:147], v[200:203], v[92:95]
	v_mfma_f32_16x16x32_bf16 v[88:91], v[160:163], v[200:203], v[88:91]
	v_mfma_f32_16x16x32_bf16 v[76:79], v[144:147], v[208:211], v[76:79]
	v_mfma_f32_16x16x32_bf16 v[72:75], v[160:163], v[208:211], v[72:75]
	v_mfma_f32_16x16x32_bf16 v[124:127], v[156:159], v[188:191], v[124:127]
	v_mfma_f32_16x16x32_bf16 v[120:123], v[164:167], v[188:191], v[120:123]
	v_mfma_f32_16x16x32_bf16 v[108:111], v[156:159], v[196:199], v[108:111]
	v_mfma_f32_16x16x32_bf16 v[104:107], v[164:167], v[196:199], v[104:107]
	v_mfma_f32_16x16x32_bf16 v[92:95], v[156:159], v[204:207], v[92:95]
	v_mfma_f32_16x16x32_bf16 v[88:91], v[164:167], v[204:207], v[88:91]
	v_mfma_f32_16x16x32_bf16 v[76:79], v[156:159], v[212:215], v[76:79]
	v_mfma_f32_16x16x32_bf16 v[72:75], v[164:167], v[212:215], v[72:75]
	s_setprio 0
	s_setprio 1
	v_mfma_f32_16x16x32_bf16 v[116:119], v[168:171], v[184:187], v[116:119]
	v_mfma_f32_16x16x32_bf16 v[112:115], v[176:179], v[184:187], v[112:115]
	v_mfma_f32_16x16x32_bf16 v[100:103], v[168:171], v[192:195], v[100:103]
	v_mfma_f32_16x16x32_bf16 v[96:99], v[176:179], v[192:195], v[96:99]
	v_mfma_f32_16x16x32_bf16 v[84:87], v[168:171], v[200:203], v[84:87]
	v_mfma_f32_16x16x32_bf16 v[80:83], v[176:179], v[200:203], v[80:83]
	v_mfma_f32_16x16x32_bf16 v[68:71], v[168:171], v[208:211], v[68:71]
	v_mfma_f32_16x16x32_bf16 v[64:67], v[176:179], v[208:211], v[64:67]
	v_mfma_f32_16x16x32_bf16 v[116:119], v[172:175], v[188:191], v[116:119]
	v_mfma_f32_16x16x32_bf16 v[112:115], v[180:183], v[188:191], v[112:115]
	v_mfma_f32_16x16x32_bf16 v[100:103], v[172:175], v[196:199], v[100:103]
	v_mfma_f32_16x16x32_bf16 v[96:99], v[180:183], v[196:199], v[96:99]
	v_mfma_f32_16x16x32_bf16 v[84:87], v[172:175], v[204:207], v[84:87]
	v_mfma_f32_16x16x32_bf16 v[80:83], v[180:183], v[204:207], v[80:83]
	v_mfma_f32_16x16x32_bf16 v[68:71], v[172:175], v[212:215], v[68:71]
	v_mfma_f32_16x16x32_bf16 v[64:67], v[180:183], v[212:215], v[64:67]
	s_setprio 0
	s_barrier
	s_add_i32 s36, s60, s45
	s_mov_b32 m0, s36
	ds_read_b128 v[184:187], v153 offset:49152
	ds_read_b128 v[188:191], v153 offset:50176
	ds_read_b128 v[192:195], v153 offset:51200
	ds_read_b128 v[196:199], v153 offset:52224
	ds_read_b128 v[200:203], v153 offset:53248
	ds_read_b128 v[204:207], v153 offset:54272
	ds_read_b128 v[208:211], v153 offset:55296
	ds_read_b128 v[212:215], v153 offset:56320
	global_load_lds_dwordx4 v130, s[98:99]
	s_add_i32 m0, s36, 0x2000
	s_add_u32 s34, s34, 0x100080
	s_addc_u32 s35, s35, 0
	s_add_i32 s36, s61, s45
	global_load_lds_dwordx4 v134, s[98:99]
	s_mov_b32 m0, s36
	s_nop 0
	global_load_lds_dwordx4 v130, s[34:35]
	s_add_i32 m0, s36, 0x2000
	s_nop 0
	global_load_lds_dwordx4 v134, s[34:35]
	s_mov_b32 m0, s50
	s_nop 0
	global_load_lds_dwordx4 v128, s[100:101]
	s_mov_b32 m0, s51
	s_nop 0
	global_load_lds_dwordx4 v132, s[100:101]
	s_waitcnt vmcnt(8)
	s_waitcnt lgkmcnt(0)
	s_barrier
	s_setprio 1
	s_waitcnt lgkmcnt(0)
	v_mfma_f32_16x16x32_bf16 v[60:63], v[144:147], v[184:187], v[60:63]
	v_mfma_f32_16x16x32_bf16 v[56:59], v[160:163], v[184:187], v[56:59]
	v_mfma_f32_16x16x32_bf16 v[44:47], v[144:147], v[192:195], v[44:47]
	v_mfma_f32_16x16x32_bf16 v[40:43], v[160:163], v[192:195], v[40:43]
	v_mfma_f32_16x16x32_bf16 v[28:31], v[144:147], v[200:203], v[28:31]
	v_mfma_f32_16x16x32_bf16 v[24:27], v[160:163], v[200:203], v[24:27]
	v_mfma_f32_16x16x32_bf16 v[12:15], v[144:147], v[208:211], v[12:15]
	v_mfma_f32_16x16x32_bf16 v[8:11], v[160:163], v[208:211], v[8:11]
	v_mfma_f32_16x16x32_bf16 v[60:63], v[156:159], v[188:191], v[60:63]
	v_mfma_f32_16x16x32_bf16 v[56:59], v[164:167], v[188:191], v[56:59]
	v_mfma_f32_16x16x32_bf16 v[44:47], v[156:159], v[196:199], v[44:47]
	v_mfma_f32_16x16x32_bf16 v[40:43], v[164:167], v[196:199], v[40:43]
	v_mfma_f32_16x16x32_bf16 v[28:31], v[156:159], v[204:207], v[28:31]
	v_mfma_f32_16x16x32_bf16 v[24:27], v[164:167], v[204:207], v[24:27]
	v_mfma_f32_16x16x32_bf16 v[12:15], v[156:159], v[212:215], v[12:15]
	v_mfma_f32_16x16x32_bf16 v[8:11], v[164:167], v[212:215], v[8:11]
	s_setprio 0
	s_setprio 1
	v_mfma_f32_16x16x32_bf16 v[52:55], v[168:171], v[184:187], v[52:55]
	v_mfma_f32_16x16x32_bf16 v[48:51], v[176:179], v[184:187], v[48:51]
	v_mfma_f32_16x16x32_bf16 v[36:39], v[168:171], v[192:195], v[36:39]
	v_mfma_f32_16x16x32_bf16 v[32:35], v[176:179], v[192:195], v[32:35]
	v_mfma_f32_16x16x32_bf16 v[20:23], v[168:171], v[200:203], v[20:23]
	v_mfma_f32_16x16x32_bf16 v[16:19], v[176:179], v[200:203], v[16:19]
	v_mfma_f32_16x16x32_bf16 v[4:7], v[168:171], v[208:211], v[4:7]
	v_mfma_f32_16x16x32_bf16 v[0:3], v[176:179], v[208:211], v[0:3]
	v_mfma_f32_16x16x32_bf16 v[52:55], v[172:175], v[188:191], v[52:55]
	v_mfma_f32_16x16x32_bf16 v[48:51], v[180:183], v[188:191], v[48:51]
	v_mfma_f32_16x16x32_bf16 v[36:39], v[172:175], v[196:199], v[36:39]
	v_mfma_f32_16x16x32_bf16 v[32:35], v[180:183], v[196:199], v[32:35]
	v_mfma_f32_16x16x32_bf16 v[20:23], v[172:175], v[204:207], v[20:23]
	v_mfma_f32_16x16x32_bf16 v[16:19], v[180:183], v[204:207], v[16:19]
	v_mfma_f32_16x16x32_bf16 v[4:7], v[172:175], v[212:215], v[4:7]
	v_mfma_f32_16x16x32_bf16 v[0:3], v[180:183], v[212:215], v[0:3]
	s_setprio 0
	s_barrier
	s_add_i32 s59, s59, 2
	s_add_u32 s57, s57, 0x100
	s_addc_u32 s58, s58, 0
	s_add_u32 s30, s30, 0x100
	s_addc_u32 s31, s31, 0
	s_cmp_gt_u32 s59, 61
	s_cbranch_scc0 .LBB0_1612
	s_and_b64 vcc, exec, s[20:21]
	s_cbranch_vccz .LBB0_1615
	s_barrier

.LBB0_1758:
	ds_read_b128 v[150:153], v147
	ds_read_b128 v[154:157], v147 offset:1024
	ds_read_b128 v[158:161], v147 offset:2048
	ds_read_b128 v[162:165], v147 offset:3072
	ds_read_b128 v[166:169], v148
	ds_read_b128 v[170:173], v148 offset:1024
	ds_read_b128 v[174:177], v148 offset:2048
	ds_read_b128 v[178:181], v148 offset:3072
	s_add_u32 s26, s24, 0xfff00080
	s_addc_u32 s27, s25, -1
	s_cmp_eq_u32 s55, 60
	s_cselect_b32 s29, s17, s27
	s_cselect_b32 s28, s51, s26
	s_cselect_b32 s27, s15, s54
	s_cselect_b32 s26, s52, s53
	s_add_i32 m0, s23, 0xc000
	ds_read_b128 v[182:185], v149
	ds_read_b128 v[186:189], v149 offset:1024
	ds_read_b128 v[190:193], v149 offset:2048
	ds_read_b128 v[194:197], v149 offset:3072
	ds_read_b128 v[198:201], v149 offset:4096
	ds_read_b128 v[202:205], v149 offset:5120
	ds_read_b128 v[206:209], v149 offset:6144
	ds_read_b128 v[210:213], v149 offset:7168
	global_load_lds_dwordx4 v138, s[24:25]
	s_add_i32 m0, s23, 0xe000
	s_nop 0
	global_load_lds_dwordx4 v136, s[24:25]
	s_waitcnt vmcnt(8)
	s_waitcnt lgkmcnt(0)
	s_barrier
	s_setprio 1
	s_waitcnt lgkmcnt(0)
	v_mfma_f32_16x16x32_bf16 v[124:127], v[150:153], v[182:185], v[124:127]
	v_mfma_f32_16x16x32_bf16 v[120:123], v[158:161], v[182:185], v[120:123]
	v_mfma_f32_16x16x32_bf16 v[108:111], v[150:153], v[190:193], v[108:111]
	v_mfma_f32_16x16x32_bf16 v[104:107], v[158:161], v[190:193], v[104:107]
	v_mfma_f32_16x16x32_bf16 v[92:95], v[150:153], v[198:201], v[92:95]
	v_mfma_f32_16x16x32_bf16 v[88:91], v[158:161], v[198:201], v[88:91]
	v_mfma_f32_16x16x32_bf16 v[76:79], v[150:153], v[206:209], v[76:79]
	v_mfma_f32_16x16x32_bf16 v[72:75], v[158:161], v[206:209], v[72:75]
	v_mfma_f32_16x16x32_bf16 v[124:127], v[154:157], v[186:189], v[124:127]
	v_mfma_f32_16x16x32_bf16 v[120:123], v[162:165], v[186:189], v[120:123]
	v_mfma_f32_16x16x32_bf16 v[108:111], v[154:157], v[194:197], v[108:111]
	v_mfma_f32_16x16x32_bf16 v[104:107], v[162:165], v[194:197], v[104:107]
	v_mfma_f32_16x16x32_bf16 v[92:95], v[154:157], v[202:205], v[92:95]
	v_mfma_f32_16x16x32_bf16 v[88:91], v[162:165], v[202:205], v[88:91]
	v_mfma_f32_16x16x32_bf16 v[76:79], v[154:157], v[210:213], v[76:79]
	v_mfma_f32_16x16x32_bf16 v[72:75], v[162:165], v[210:213], v[72:75]
	s_setprio 0
	s_setprio 1
	v_mfma_f32_16x16x32_bf16 v[116:119], v[166:169], v[182:185], v[116:119]
	v_mfma_f32_16x16x32_bf16 v[112:115], v[174:177], v[182:185], v[112:115]
	v_mfma_f32_16x16x32_bf16 v[100:103], v[166:169], v[190:193], v[100:103]
	v_mfma_f32_16x16x32_bf16 v[96:99], v[174:177], v[190:193], v[96:99]
	v_mfma_f32_16x16x32_bf16 v[84:87], v[166:169], v[198:201], v[84:87]
	v_mfma_f32_16x16x32_bf16 v[80:83], v[174:177], v[198:201], v[80:83]
	v_mfma_f32_16x16x32_bf16 v[68:71], v[166:169], v[206:209], v[68:71]
	v_mfma_f32_16x16x32_bf16 v[64:67], v[174:177], v[206:209], v[64:67]
	v_mfma_f32_16x16x32_bf16 v[116:119], v[170:173], v[186:189], v[116:119]
	v_mfma_f32_16x16x32_bf16 v[112:115], v[178:181], v[186:189], v[112:115]
	v_mfma_f32_16x16x32_bf16 v[100:103], v[170:173], v[194:197], v[100:103]
	v_mfma_f32_16x16x32_bf16 v[96:99], v[178:181], v[194:197], v[96:99]
	v_mfma_f32_16x16x32_bf16 v[84:87], v[170:173], v[202:205], v[84:87]
	v_mfma_f32_16x16x32_bf16 v[80:83], v[178:181], v[202:205], v[80:83]
	v_mfma_f32_16x16x32_bf16 v[68:71], v[170:173], v[210:213], v[68:71]
	v_mfma_f32_16x16x32_bf16 v[64:67], v[178:181], v[210:213], v[64:67]
	s_setprio 0
	s_barrier
	s_add_u32 s98, s26, 0x80
	s_addc_u32 s99, s27, 0
	s_add_u32 s100, s28, 0x80
	s_addc_u32 s101, s29, 0
	s_add_i32 s56, s47, s39
	s_mov_b32 m0, s56
	ds_read_b128 v[182:185], v149 offset:16384
	ds_read_b128 v[186:189], v149 offset:17408
	ds_read_b128 v[190:193], v149 offset:18432
	ds_read_b128 v[194:197], v149 offset:19456
	ds_read_b128 v[198:201], v149 offset:20480
	ds_read_b128 v[202:205], v149 offset:21504
	ds_read_b128 v[206:209], v149 offset:22528
	ds_read_b128 v[210:213], v149 offset:23552
	global_load_lds_dwordx4 v132, s[26:27]
	s_add_i32 m0, s56, 0x2000
	s_add_u32 s56, s26, 0x100000
	s_addc_u32 s57, s27, 0
	s_add_i32 s58, s48, s39
	global_load_lds_dwordx4 v128, s[26:27]
	s_mov_b32 m0, s58
	s_nop 0
	global_load_lds_dwordx4 v132, s[56:57]
	s_add_i32 m0, s58, 0x2000
	s_nop 0
	global_load_lds_dwordx4 v128, s[56:57]
	s_mov_b32 m0, s23
	s_nop 0
	global_load_lds_dwordx4 v134, s[28:29]
	s_mov_b32 m0, s41
	s_nop 0
	global_load_lds_dwordx4 v130, s[28:29]
	s_waitcnt vmcnt(8)
	s_waitcnt lgkmcnt(0)
	s_barrier
	s_setprio 1
	s_waitcnt lgkmcnt(0)
	v_mfma_f32_16x16x32_bf16 v[60:63], v[150:153], v[182:185], v[60:63]
	v_mfma_f32_16x16x32_bf16 v[56:59], v[158:161], v[182:185], v[56:59]
	v_mfma_f32_16x16x32_bf16 v[44:47], v[150:153], v[190:193], v[44:47]
	v_mfma_f32_16x16x32_bf16 v[40:43], v[158:161], v[190:193], v[40:43]
	v_mfma_f32_16x16x32_bf16 v[28:31], v[150:153], v[198:201], v[28:31]
	v_mfma_f32_16x16x32_bf16 v[24:27], v[158:161], v[198:201], v[24:27]
	v_mfma_f32_16x16x32_bf16 v[12:15], v[150:153], v[206:209], v[12:15]
	v_mfma_f32_16x16x32_bf16 v[8:11], v[158:161], v[206:209], v[8:11]
	v_mfma_f32_16x16x32_bf16 v[60:63], v[154:157], v[186:189], v[60:63]
	v_mfma_f32_16x16x32_bf16 v[56:59], v[162:165], v[186:189], v[56:59]
	v_mfma_f32_16x16x32_bf16 v[44:47], v[154:157], v[194:197], v[44:47]
	v_mfma_f32_16x16x32_bf16 v[40:43], v[162:165], v[194:197], v[40:43]
	v_mfma_f32_16x16x32_bf16 v[28:31], v[154:157], v[202:205], v[28:31]
	v_mfma_f32_16x16x32_bf16 v[24:27], v[162:165], v[202:205], v[24:27]
	v_mfma_f32_16x16x32_bf16 v[12:15], v[154:157], v[210:213], v[12:15]
	v_mfma_f32_16x16x32_bf16 v[8:11], v[162:165], v[210:213], v[8:11]
	s_setprio 0
	s_setprio 1
	v_mfma_f32_16x16x32_bf16 v[52:55], v[166:169], v[182:185], v[52:55]
	v_mfma_f32_16x16x32_bf16 v[48:51], v[174:177], v[182:185], v[48:51]
	v_mfma_f32_16x16x32_bf16 v[36:39], v[166:169], v[190:193], v[36:39]
	v_mfma_f32_16x16x32_bf16 v[32:35], v[174:177], v[190:193], v[32:35]
	v_mfma_f32_16x16x32_bf16 v[20:23], v[166:169], v[198:201], v[20:23]
	v_mfma_f32_16x16x32_bf16 v[16:19], v[174:177], v[198:201], v[16:19]
	v_mfma_f32_16x16x32_bf16 v[4:7], v[166:169], v[206:209], v[4:7]
	v_mfma_f32_16x16x32_bf16 v[0:3], v[174:177], v[206:209], v[0:3]
	v_mfma_f32_16x16x32_bf16 v[52:55], v[170:173], v[186:189], v[52:55]
	v_mfma_f32_16x16x32_bf16 v[48:51], v[178:181], v[186:189], v[48:51]
	v_mfma_f32_16x16x32_bf16 v[36:39], v[170:173], v[194:197], v[36:39]
	v_mfma_f32_16x16x32_bf16 v[32:35], v[178:181], v[194:197], v[32:35]
	v_mfma_f32_16x16x32_bf16 v[20:23], v[170:173], v[202:205], v[20:23]
	v_mfma_f32_16x16x32_bf16 v[16:19], v[178:181], v[202:205], v[16:19]
	v_mfma_f32_16x16x32_bf16 v[4:7], v[170:173], v[210:213], v[4:7]
	v_mfma_f32_16x16x32_bf16 v[0:3], v[178:181], v[210:213], v[0:3]
	s_setprio 0
	s_barrier
	s_add_i32 s56, 0, 0x18000
	s_add_i32 s57, 0, 0x1c000
	v_add_u32_e32 v162, s56, v145
	v_add_u32_e32 v178, s57, v145
	ds_read_b128 v[150:153], v162
	ds_read_b128 v[154:157], v162 offset:1024
	ds_read_b128 v[158:161], v162 offset:2048
	ds_read_b128 v[162:165], v162 offset:3072
	ds_read_b128 v[166:169], v178
	ds_read_b128 v[170:173], v178 offset:1024
	ds_read_b128 v[174:177], v178 offset:2048
	ds_read_b128 v[178:181], v178 offset:3072
	s_add_u32 s28, s28, 0x100000
	s_addc_u32 s29, s29, 0
	s_mov_b32 m0, s42
	ds_read_b128 v[182:185], v149 offset:32768
	ds_read_b128 v[186:189], v149 offset:33792
	ds_read_b128 v[190:193], v149 offset:34816
	ds_read_b128 v[194:197], v149 offset:35840
	ds_read_b128 v[198:201], v149 offset:36864
	ds_read_b128 v[202:205], v149 offset:37888
	ds_read_b128 v[206:209], v149 offset:38912
	ds_read_b128 v[210:213], v149 offset:39936
	global_load_lds_dwordx4 v134, s[28:29]
	s_mov_b32 m0, s43
	s_nop 0
	global_load_lds_dwordx4 v130, s[28:29]
	s_waitcnt vmcnt(8)
	s_waitcnt lgkmcnt(0)
	s_barrier
	s_setprio 1
	s_waitcnt lgkmcnt(0)
	v_mfma_f32_16x16x32_bf16 v[124:127], v[150:153], v[182:185], v[124:127]
	v_mfma_f32_16x16x32_bf16 v[120:123], v[158:161], v[182:185], v[120:123]
	v_mfma_f32_16x16x32_bf16 v[108:111], v[150:153], v[190:193], v[108:111]
	v_mfma_f32_16x16x32_bf16 v[104:107], v[158:161], v[190:193], v[104:107]
	v_mfma_f32_16x16x32_bf16 v[92:95], v[150:153], v[198:201], v[92:95]
	v_mfma_f32_16x16x32_bf16 v[88:91], v[158:161], v[198:201], v[88:91]
	v_mfma_f32_16x16x32_bf16 v[76:79], v[150:153], v[206:209], v[76:79]
	v_mfma_f32_16x16x32_bf16 v[72:75], v[158:161], v[206:209], v[72:75]
	v_mfma_f32_16x16x32_bf16 v[124:127], v[154:157], v[186:189], v[124:127]
	v_mfma_f32_16x16x32_bf16 v[120:123], v[162:165], v[186:189], v[120:123]
	v_mfma_f32_16x16x32_bf16 v[108:111], v[154:157], v[194:197], v[108:111]
	v_mfma_f32_16x16x32_bf16 v[104:107], v[162:165], v[194:197], v[104:107]
	v_mfma_f32_16x16x32_bf16 v[92:95], v[154:157], v[202:205], v[92:95]
	v_mfma_f32_16x16x32_bf16 v[88:91], v[162:165], v[202:205], v[88:91]
	v_mfma_f32_16x16x32_bf16 v[76:79], v[154:157], v[210:213], v[76:79]
	v_mfma_f32_16x16x32_bf16 v[72:75], v[162:165], v[210:213], v[72:75]
	s_setprio 0
	s_setprio 1
	v_mfma_f32_16x16x32_bf16 v[116:119], v[166:169], v[182:185], v[116:119]
	v_mfma_f32_16x16x32_bf16 v[112:115], v[174:177], v[182:185], v[112:115]
	v_mfma_f32_16x16x32_bf16 v[100:103], v[166:169], v[190:193], v[100:103]
	v_mfma_f32_16x16x32_bf16 v[96:99], v[174:177], v[190:193], v[96:99]
	v_mfma_f32_16x16x32_bf16 v[84:87], v[166:169], v[198:201], v[84:87]
	v_mfma_f32_16x16x32_bf16 v[80:83], v[174:177], v[198:201], v[80:83]
	v_mfma_f32_16x16x32_bf16 v[68:71], v[166:169], v[206:209], v[68:71]
	v_mfma_f32_16x16x32_bf16 v[64:67], v[174:177], v[206:209], v[64:67]
	v_mfma_f32_16x16x32_bf16 v[116:119], v[170:173], v[186:189], v[116:119]
	v_mfma_f32_16x16x32_bf16 v[112:115], v[178:181], v[186:189], v[112:115]
	v_mfma_f32_16x16x32_bf16 v[100:103], v[170:173], v[194:197], v[100:103]
	v_mfma_f32_16x16x32_bf16 v[96:99], v[178:181], v[194:197], v[96:99]
	v_mfma_f32_16x16x32_bf16 v[84:87], v[170:173], v[202:205], v[84:87]
	v_mfma_f32_16x16x32_bf16 v[80:83], v[178:181], v[202:205], v[80:83]
	v_mfma_f32_16x16x32_bf16 v[68:71], v[170:173], v[210:213], v[68:71]
	v_mfma_f32_16x16x32_bf16 v[64:67], v[178:181], v[210:213], v[64:67]
	s_setprio 0
	s_barrier
	s_add_i32 s28, s56, s39
	s_mov_b32 m0, s28
	ds_read_b128 v[182:185], v149 offset:49152
	ds_read_b128 v[186:189], v149 offset:50176
	ds_read_b128 v[190:193], v149 offset:51200
	ds_read_b128 v[194:197], v149 offset:52224
	ds_read_b128 v[198:201], v149 offset:53248
	ds_read_b128 v[202:205], v149 offset:54272
	ds_read_b128 v[206:209], v149 offset:55296
	ds_read_b128 v[210:213], v149 offset:56320
	global_load_lds_dwordx4 v132, s[98:99]
	s_add_i32 m0, s28, 0x2000
	s_add_u32 s26, s26, 0x100080
	s_addc_u32 s27, s27, 0
	s_add_i32 s28, s57, s39
	global_load_lds_dwordx4 v128, s[98:99]
	s_mov_b32 m0, s28
	s_nop 0
	global_load_lds_dwordx4 v132, s[26:27]
	s_add_i32 m0, s28, 0x2000
	s_nop 0
	global_load_lds_dwordx4 v128, s[26:27]
	s_mov_b32 m0, s44
	s_nop 0
	global_load_lds_dwordx4 v134, s[100:101]
	s_mov_b32 m0, s45
	s_nop 0
	global_load_lds_dwordx4 v130, s[100:101]
	s_waitcnt vmcnt(8)
	s_waitcnt lgkmcnt(0)
	s_barrier
	s_setprio 1
	s_waitcnt lgkmcnt(0)
	v_mfma_f32_16x16x32_bf16 v[60:63], v[150:153], v[182:185], v[60:63]
	v_mfma_f32_16x16x32_bf16 v[56:59], v[158:161], v[182:185], v[56:59]
	v_mfma_f32_16x16x32_bf16 v[44:47], v[150:153], v[190:193], v[44:47]
	v_mfma_f32_16x16x32_bf16 v[40:43], v[158:161], v[190:193], v[40:43]
	v_mfma_f32_16x16x32_bf16 v[28:31], v[150:153], v[198:201], v[28:31]
	v_mfma_f32_16x16x32_bf16 v[24:27], v[158:161], v[198:201], v[24:27]
	v_mfma_f32_16x16x32_bf16 v[12:15], v[150:153], v[206:209], v[12:15]
	v_mfma_f32_16x16x32_bf16 v[8:11], v[158:161], v[206:209], v[8:11]
	v_mfma_f32_16x16x32_bf16 v[60:63], v[154:157], v[186:189], v[60:63]
	v_mfma_f32_16x16x32_bf16 v[56:59], v[162:165], v[186:189], v[56:59]
	v_mfma_f32_16x16x32_bf16 v[44:47], v[154:157], v[194:197], v[44:47]
	v_mfma_f32_16x16x32_bf16 v[40:43], v[162:165], v[194:197], v[40:43]
	v_mfma_f32_16x16x32_bf16 v[28:31], v[154:157], v[202:205], v[28:31]
	v_mfma_f32_16x16x32_bf16 v[24:27], v[162:165], v[202:205], v[24:27]
	v_mfma_f32_16x16x32_bf16 v[12:15], v[154:157], v[210:213], v[12:15]
	v_mfma_f32_16x16x32_bf16 v[8:11], v[162:165], v[210:213], v[8:11]
	s_setprio 0
	s_setprio 1
	v_mfma_f32_16x16x32_bf16 v[52:55], v[166:169], v[182:185], v[52:55]
	v_mfma_f32_16x16x32_bf16 v[48:51], v[174:177], v[182:185], v[48:51]
	v_mfma_f32_16x16x32_bf16 v[36:39], v[166:169], v[190:193], v[36:39]
	v_mfma_f32_16x16x32_bf16 v[32:35], v[174:177], v[190:193], v[32:35]
	v_mfma_f32_16x16x32_bf16 v[20:23], v[166:169], v[198:201], v[20:23]
	v_mfma_f32_16x16x32_bf16 v[16:19], v[174:177], v[198:201], v[16:19]
	v_mfma_f32_16x16x32_bf16 v[4:7], v[166:169], v[206:209], v[4:7]
	v_mfma_f32_16x16x32_bf16 v[0:3], v[174:177], v[206:209], v[0:3]
	v_mfma_f32_16x16x32_bf16 v[52:55], v[170:173], v[186:189], v[52:55]
	v_mfma_f32_16x16x32_bf16 v[48:51], v[178:181], v[186:189], v[48:51]
	v_mfma_f32_16x16x32_bf16 v[36:39], v[170:173], v[194:197], v[36:39]
	v_mfma_f32_16x16x32_bf16 v[32:35], v[178:181], v[194:197], v[32:35]
	v_mfma_f32_16x16x32_bf16 v[20:23], v[170:173], v[202:205], v[20:23]
	v_mfma_f32_16x16x32_bf16 v[16:19], v[178:181], v[202:205], v[16:19]
	v_mfma_f32_16x16x32_bf16 v[4:7], v[170:173], v[210:213], v[4:7]
	v_mfma_f32_16x16x32_bf16 v[0:3], v[178:181], v[210:213], v[0:3]
	s_setprio 0
	s_barrier
	s_add_i32 s55, s55, 2
	s_add_u32 s53, s53, 0x100
	s_addc_u32 s54, s54, 0
	s_add_u32 s24, s24, 0x100
	s_addc_u32 s25, s25, 0
	s_cmp_gt_u32 s55, 61
	s_cbranch_scc0 .LBB0_1758
	s_and_b64 vcc, exec, s[12:13]
	s_cbranch_vccz .LBB0_1761
	s_barrier

.LBB0_1963:
	ds_read_b128 v[144:147], v151
	ds_read_b128 v[156:159], v151 offset:1024
	ds_read_b128 v[160:163], v151 offset:2048
	ds_read_b128 v[164:167], v151 offset:3072
	ds_read_b128 v[168:171], v152
	ds_read_b128 v[172:175], v152 offset:1024
	ds_read_b128 v[176:179], v152 offset:2048
	ds_read_b128 v[180:183], v152 offset:3072
	s_add_u32 s28, s26, 0x100
	s_addc_u32 s29, s27, 0
	s_cmpk_eq_i32 s59, 0xa8
	s_cselect_b32 s35, s7, s29
	s_cselect_b32 s34, s6, s28
	s_cselect_b32 s31, s25, s58
	s_cselect_b32 s30, s24, s57
	s_add_i32 m0, s43, 0xc000
	ds_read_b128 v[184:187], v153
	ds_read_b128 v[188:191], v153 offset:1024
	ds_read_b128 v[192:195], v153 offset:2048
	ds_read_b128 v[196:199], v153 offset:3072
	ds_read_b128 v[200:203], v153 offset:4096
	ds_read_b128 v[204:207], v153 offset:5120
	ds_read_b128 v[208:211], v153 offset:6144
	ds_read_b128 v[212:215], v153 offset:7168
	global_load_lds_dwordx4 v138, s[26:27]
	s_add_i32 m0, s43, 0xe000
	s_nop 0
	global_load_lds_dwordx4 v136, s[26:27]
	s_waitcnt vmcnt(8)
	s_waitcnt lgkmcnt(0)
	s_barrier
	s_setprio 1
	s_waitcnt lgkmcnt(0)
	v_mfma_f32_16x16x32_bf16 v[124:127], v[144:147], v[184:187], v[124:127]
	v_mfma_f32_16x16x32_bf16 v[120:123], v[160:163], v[184:187], v[120:123]
	v_mfma_f32_16x16x32_bf16 v[108:111], v[144:147], v[192:195], v[108:111]
	v_mfma_f32_16x16x32_bf16 v[104:107], v[160:163], v[192:195], v[104:107]
	v_mfma_f32_16x16x32_bf16 v[92:95], v[144:147], v[200:203], v[92:95]
	v_mfma_f32_16x16x32_bf16 v[88:91], v[160:163], v[200:203], v[88:91]
	v_mfma_f32_16x16x32_bf16 v[76:79], v[144:147], v[208:211], v[76:79]
	v_mfma_f32_16x16x32_bf16 v[72:75], v[160:163], v[208:211], v[72:75]
	v_mfma_f32_16x16x32_bf16 v[124:127], v[156:159], v[188:191], v[124:127]
	v_mfma_f32_16x16x32_bf16 v[120:123], v[164:167], v[188:191], v[120:123]
	v_mfma_f32_16x16x32_bf16 v[108:111], v[156:159], v[196:199], v[108:111]
	v_mfma_f32_16x16x32_bf16 v[104:107], v[164:167], v[196:199], v[104:107]
	v_mfma_f32_16x16x32_bf16 v[92:95], v[156:159], v[204:207], v[92:95]
	v_mfma_f32_16x16x32_bf16 v[88:91], v[164:167], v[204:207], v[88:91]
	v_mfma_f32_16x16x32_bf16 v[76:79], v[156:159], v[212:215], v[76:79]
	v_mfma_f32_16x16x32_bf16 v[72:75], v[164:167], v[212:215], v[72:75]
	s_setprio 0
	s_setprio 1
	v_mfma_f32_16x16x32_bf16 v[116:119], v[168:171], v[184:187], v[116:119]
	v_mfma_f32_16x16x32_bf16 v[112:115], v[176:179], v[184:187], v[112:115]
	v_mfma_f32_16x16x32_bf16 v[100:103], v[168:171], v[192:195], v[100:103]
	v_mfma_f32_16x16x32_bf16 v[96:99], v[176:179], v[192:195], v[96:99]
	v_mfma_f32_16x16x32_bf16 v[84:87], v[168:171], v[200:203], v[84:87]
	v_mfma_f32_16x16x32_bf16 v[80:83], v[176:179], v[200:203], v[80:83]
	v_mfma_f32_16x16x32_bf16 v[68:71], v[168:171], v[208:211], v[68:71]
	v_mfma_f32_16x16x32_bf16 v[64:67], v[176:179], v[208:211], v[64:67]
	v_mfma_f32_16x16x32_bf16 v[116:119], v[172:175], v[188:191], v[116:119]
	v_mfma_f32_16x16x32_bf16 v[112:115], v[180:183], v[188:191], v[112:115]
	v_mfma_f32_16x16x32_bf16 v[100:103], v[172:175], v[196:199], v[100:103]
	v_mfma_f32_16x16x32_bf16 v[96:99], v[180:183], v[196:199], v[96:99]
	v_mfma_f32_16x16x32_bf16 v[84:87], v[172:175], v[204:207], v[84:87]
	v_mfma_f32_16x16x32_bf16 v[80:83], v[180:183], v[204:207], v[80:83]
	v_mfma_f32_16x16x32_bf16 v[68:71], v[172:175], v[212:215], v[68:71]
	v_mfma_f32_16x16x32_bf16 v[64:67], v[180:183], v[212:215], v[64:67]
	s_setprio 0
	s_barrier
	s_add_u32 s98, s30, 0x80
	s_addc_u32 s99, s31, 0
	s_add_u32 s100, s34, 0x80
	s_addc_u32 s101, s35, 0
	s_add_i32 s26, s52, s42
	s_mov_b32 m0, s26
	ds_read_b128 v[184:187], v153 offset:16384
	ds_read_b128 v[188:191], v153 offset:17408
	ds_read_b128 v[192:195], v153 offset:18432
	ds_read_b128 v[196:199], v153 offset:19456
	ds_read_b128 v[200:203], v153 offset:20480
	ds_read_b128 v[204:207], v153 offset:21504
	ds_read_b128 v[208:211], v153 offset:22528
	ds_read_b128 v[212:215], v153 offset:23552
	global_load_lds_dwordx4 v130, s[30:31]
	s_add_i32 m0, s26, 0x2000
	s_add_u32 s26, s30, 0x2b0000
	s_addc_u32 s27, s31, 0
	s_add_i32 s60, s53, s42
	global_load_lds_dwordx4 v134, s[30:31]
	s_mov_b32 m0, s60
	s_nop 0
	global_load_lds_dwordx4 v130, s[26:27]
	s_add_i32 m0, s60, 0x2000
	s_nop 0
	global_load_lds_dwordx4 v134, s[26:27]
	s_mov_b32 m0, s43
	s_nop 0
	global_load_lds_dwordx4 v128, s[34:35]
	s_mov_b32 m0, s44
	s_nop 0
	global_load_lds_dwordx4 v132, s[34:35]
	s_waitcnt vmcnt(8)
	s_waitcnt lgkmcnt(0)
	s_barrier
	s_setprio 1
	s_waitcnt lgkmcnt(0)
	v_mfma_f32_16x16x32_bf16 v[60:63], v[144:147], v[184:187], v[60:63]
	v_mfma_f32_16x16x32_bf16 v[56:59], v[160:163], v[184:187], v[56:59]
	v_mfma_f32_16x16x32_bf16 v[44:47], v[144:147], v[192:195], v[44:47]
	v_mfma_f32_16x16x32_bf16 v[40:43], v[160:163], v[192:195], v[40:43]
	v_mfma_f32_16x16x32_bf16 v[28:31], v[144:147], v[200:203], v[28:31]
	v_mfma_f32_16x16x32_bf16 v[24:27], v[160:163], v[200:203], v[24:27]
	v_mfma_f32_16x16x32_bf16 v[12:15], v[144:147], v[208:211], v[12:15]
	v_mfma_f32_16x16x32_bf16 v[8:11], v[160:163], v[208:211], v[8:11]
	v_mfma_f32_16x16x32_bf16 v[60:63], v[156:159], v[188:191], v[60:63]
	v_mfma_f32_16x16x32_bf16 v[56:59], v[164:167], v[188:191], v[56:59]
	v_mfma_f32_16x16x32_bf16 v[44:47], v[156:159], v[196:199], v[44:47]
	v_mfma_f32_16x16x32_bf16 v[40:43], v[164:167], v[196:199], v[40:43]
	v_mfma_f32_16x16x32_bf16 v[28:31], v[156:159], v[204:207], v[28:31]
	v_mfma_f32_16x16x32_bf16 v[24:27], v[164:167], v[204:207], v[24:27]
	v_mfma_f32_16x16x32_bf16 v[12:15], v[156:159], v[212:215], v[12:15]
	v_mfma_f32_16x16x32_bf16 v[8:11], v[164:167], v[212:215], v[8:11]
	s_setprio 0
	s_setprio 1
	v_mfma_f32_16x16x32_bf16 v[52:55], v[168:171], v[184:187], v[52:55]
	v_mfma_f32_16x16x32_bf16 v[48:51], v[176:179], v[184:187], v[48:51]
	v_mfma_f32_16x16x32_bf16 v[36:39], v[168:171], v[192:195], v[36:39]
	v_mfma_f32_16x16x32_bf16 v[32:35], v[176:179], v[192:195], v[32:35]
	v_mfma_f32_16x16x32_bf16 v[20:23], v[168:171], v[200:203], v[20:23]
	v_mfma_f32_16x16x32_bf16 v[16:19], v[176:179], v[200:203], v[16:19]
	v_mfma_f32_16x16x32_bf16 v[4:7], v[168:171], v[208:211], v[4:7]
	v_mfma_f32_16x16x32_bf16 v[0:3], v[176:179], v[208:211], v[0:3]
	v_mfma_f32_16x16x32_bf16 v[52:55], v[172:175], v[188:191], v[52:55]
	v_mfma_f32_16x16x32_bf16 v[48:51], v[180:183], v[188:191], v[48:51]
	v_mfma_f32_16x16x32_bf16 v[36:39], v[172:175], v[196:199], v[36:39]
	v_mfma_f32_16x16x32_bf16 v[32:35], v[180:183], v[196:199], v[32:35]
	v_mfma_f32_16x16x32_bf16 v[20:23], v[172:175], v[204:207], v[20:23]
	v_mfma_f32_16x16x32_bf16 v[16:19], v[180:183], v[204:207], v[16:19]
	v_mfma_f32_16x16x32_bf16 v[4:7], v[172:175], v[212:215], v[4:7]
	v_mfma_f32_16x16x32_bf16 v[0:3], v[180:183], v[212:215], v[0:3]
	s_setprio 0
	s_barrier
	s_add_i32 s60, 0, 0x18000
	v_add_u32_e32 v155, s60, v149
	s_add_i32 s61, 0, 0x1c000
	ds_read_b128 v[144:147], v155
	ds_read_b128 v[156:159], v155 offset:1024
	ds_read_b128 v[160:163], v155 offset:2048
	ds_read_b128 v[164:167], v155 offset:3072
	v_add_u32_e32 v155, s61, v149
	ds_read_b128 v[168:171], v155
	ds_read_b128 v[172:175], v155 offset:1024
	ds_read_b128 v[176:179], v155 offset:2048
	ds_read_b128 v[180:183], v155 offset:3072
	s_add_u32 s26, s34, 0x2b0000
	s_addc_u32 s27, s35, 0
	s_mov_b32 m0, s45
	ds_read_b128 v[184:187], v153 offset:32768
	ds_read_b128 v[188:191], v153 offset:33792
	ds_read_b128 v[192:195], v153 offset:34816
	ds_read_b128 v[196:199], v153 offset:35840
	ds_read_b128 v[200:203], v153 offset:36864
	ds_read_b128 v[204:207], v153 offset:37888
	ds_read_b128 v[208:211], v153 offset:38912
	ds_read_b128 v[212:215], v153 offset:39936
	global_load_lds_dwordx4 v128, s[26:27]
	s_mov_b32 m0, s46
	s_nop 0
	global_load_lds_dwordx4 v132, s[26:27]
	s_waitcnt vmcnt(8)
	s_waitcnt lgkmcnt(0)
	s_barrier
	s_setprio 1
	s_waitcnt lgkmcnt(0)
	v_mfma_f32_16x16x32_bf16 v[124:127], v[144:147], v[184:187], v[124:127]
	v_mfma_f32_16x16x32_bf16 v[120:123], v[160:163], v[184:187], v[120:123]
	v_mfma_f32_16x16x32_bf16 v[108:111], v[144:147], v[192:195], v[108:111]
	v_mfma_f32_16x16x32_bf16 v[104:107], v[160:163], v[192:195], v[104:107]
	v_mfma_f32_16x16x32_bf16 v[92:95], v[144:147], v[200:203], v[92:95]
	v_mfma_f32_16x16x32_bf16 v[88:91], v[160:163], v[200:203], v[88:91]
	v_mfma_f32_16x16x32_bf16 v[76:79], v[144:147], v[208:211], v[76:79]
	v_mfma_f32_16x16x32_bf16 v[72:75], v[160:163], v[208:211], v[72:75]
	v_mfma_f32_16x16x32_bf16 v[124:127], v[156:159], v[188:191], v[124:127]
	v_mfma_f32_16x16x32_bf16 v[120:123], v[164:167], v[188:191], v[120:123]
	v_mfma_f32_16x16x32_bf16 v[108:111], v[156:159], v[196:199], v[108:111]
	v_mfma_f32_16x16x32_bf16 v[104:107], v[164:167], v[196:199], v[104:107]
	v_mfma_f32_16x16x32_bf16 v[92:95], v[156:159], v[204:207], v[92:95]
	v_mfma_f32_16x16x32_bf16 v[88:91], v[164:167], v[204:207], v[88:91]
	v_mfma_f32_16x16x32_bf16 v[76:79], v[156:159], v[212:215], v[76:79]
	v_mfma_f32_16x16x32_bf16 v[72:75], v[164:167], v[212:215], v[72:75]
	s_setprio 0
	s_setprio 1
	v_mfma_f32_16x16x32_bf16 v[116:119], v[168:171], v[184:187], v[116:119]
	v_mfma_f32_16x16x32_bf16 v[112:115], v[176:179], v[184:187], v[112:115]
	v_mfma_f32_16x16x32_bf16 v[100:103], v[168:171], v[192:195], v[100:103]
	v_mfma_f32_16x16x32_bf16 v[96:99], v[176:179], v[192:195], v[96:99]
	v_mfma_f32_16x16x32_bf16 v[84:87], v[168:171], v[200:203], v[84:87]
	v_mfma_f32_16x16x32_bf16 v[80:83], v[176:179], v[200:203], v[80:83]
	v_mfma_f32_16x16x32_bf16 v[68:71], v[168:171], v[208:211], v[68:71]
	v_mfma_f32_16x16x32_bf16 v[64:67], v[176:179], v[208:211], v[64:67]
	v_mfma_f32_16x16x32_bf16 v[116:119], v[172:175], v[188:191], v[116:119]
	v_mfma_f32_16x16x32_bf16 v[112:115], v[180:183], v[188:191], v[112:115]
	v_mfma_f32_16x16x32_bf16 v[100:103], v[172:175], v[196:199], v[100:103]
	v_mfma_f32_16x16x32_bf16 v[96:99], v[180:183], v[196:199], v[96:99]
	v_mfma_f32_16x16x32_bf16 v[84:87], v[172:175], v[204:207], v[84:87]
	v_mfma_f32_16x16x32_bf16 v[80:83], v[180:183], v[204:207], v[80:83]
	v_mfma_f32_16x16x32_bf16 v[68:71], v[172:175], v[212:215], v[68:71]
	v_mfma_f32_16x16x32_bf16 v[64:67], v[180:183], v[212:215], v[64:67]
	s_setprio 0
	s_barrier
	s_add_i32 s26, s60, s42
	s_mov_b32 m0, s26
	ds_read_b128 v[184:187], v153 offset:49152
	ds_read_b128 v[188:191], v153 offset:50176
	ds_read_b128 v[192:195], v153 offset:51200
	ds_read_b128 v[196:199], v153 offset:52224
	ds_read_b128 v[200:203], v153 offset:53248
	ds_read_b128 v[204:207], v153 offset:54272
	ds_read_b128 v[208:211], v153 offset:55296
	ds_read_b128 v[212:215], v153 offset:56320
	global_load_lds_dwordx4 v130, s[98:99]
	s_add_i32 m0, s26, 0x2000
	s_add_u32 s26, s30, 0x2b0080
	s_addc_u32 s27, s31, 0
	s_add_i32 s30, s61, s42
	global_load_lds_dwordx4 v134, s[98:99]
	s_mov_b32 m0, s30
	s_nop 0
	global_load_lds_dwordx4 v130, s[26:27]
	s_add_i32 m0, s30, 0x2000
	s_nop 0
	global_load_lds_dwordx4 v134, s[26:27]
	s_mov_b32 m0, s50
	s_nop 0
	global_load_lds_dwordx4 v128, s[100:101]
	s_mov_b32 m0, s51
	s_nop 0
	global_load_lds_dwordx4 v132, s[100:101]
	s_waitcnt vmcnt(8)
	s_waitcnt lgkmcnt(0)
	s_barrier
	s_setprio 1
	s_waitcnt lgkmcnt(0)
	v_mfma_f32_16x16x32_bf16 v[60:63], v[144:147], v[184:187], v[60:63]
	v_mfma_f32_16x16x32_bf16 v[56:59], v[160:163], v[184:187], v[56:59]
	v_mfma_f32_16x16x32_bf16 v[44:47], v[144:147], v[192:195], v[44:47]
	v_mfma_f32_16x16x32_bf16 v[40:43], v[160:163], v[192:195], v[40:43]
	v_mfma_f32_16x16x32_bf16 v[28:31], v[144:147], v[200:203], v[28:31]
	v_mfma_f32_16x16x32_bf16 v[24:27], v[160:163], v[200:203], v[24:27]
	v_mfma_f32_16x16x32_bf16 v[12:15], v[144:147], v[208:211], v[12:15]
	v_mfma_f32_16x16x32_bf16 v[8:11], v[160:163], v[208:211], v[8:11]
	v_mfma_f32_16x16x32_bf16 v[60:63], v[156:159], v[188:191], v[60:63]
	v_mfma_f32_16x16x32_bf16 v[56:59], v[164:167], v[188:191], v[56:59]
	v_mfma_f32_16x16x32_bf16 v[44:47], v[156:159], v[196:199], v[44:47]
	v_mfma_f32_16x16x32_bf16 v[40:43], v[164:167], v[196:199], v[40:43]
	v_mfma_f32_16x16x32_bf16 v[28:31], v[156:159], v[204:207], v[28:31]
	v_mfma_f32_16x16x32_bf16 v[24:27], v[164:167], v[204:207], v[24:27]
	v_mfma_f32_16x16x32_bf16 v[12:15], v[156:159], v[212:215], v[12:15]
	v_mfma_f32_16x16x32_bf16 v[8:11], v[164:167], v[212:215], v[8:11]
	s_setprio 0
	s_setprio 1
	v_mfma_f32_16x16x32_bf16 v[52:55], v[168:171], v[184:187], v[52:55]
	v_mfma_f32_16x16x32_bf16 v[48:51], v[176:179], v[184:187], v[48:51]
	v_mfma_f32_16x16x32_bf16 v[36:39], v[168:171], v[192:195], v[36:39]
	v_mfma_f32_16x16x32_bf16 v[32:35], v[176:179], v[192:195], v[32:35]
	v_mfma_f32_16x16x32_bf16 v[20:23], v[168:171], v[200:203], v[20:23]
	v_mfma_f32_16x16x32_bf16 v[16:19], v[176:179], v[200:203], v[16:19]
	v_mfma_f32_16x16x32_bf16 v[4:7], v[168:171], v[208:211], v[4:7]
	v_mfma_f32_16x16x32_bf16 v[0:3], v[176:179], v[208:211], v[0:3]
	v_mfma_f32_16x16x32_bf16 v[52:55], v[172:175], v[188:191], v[52:55]
	v_mfma_f32_16x16x32_bf16 v[48:51], v[180:183], v[188:191], v[48:51]
	v_mfma_f32_16x16x32_bf16 v[36:39], v[172:175], v[196:199], v[36:39]
	v_mfma_f32_16x16x32_bf16 v[32:35], v[180:183], v[196:199], v[32:35]
	v_mfma_f32_16x16x32_bf16 v[20:23], v[172:175], v[204:207], v[20:23]
	v_mfma_f32_16x16x32_bf16 v[16:19], v[180:183], v[204:207], v[16:19]
	v_mfma_f32_16x16x32_bf16 v[4:7], v[172:175], v[212:215], v[4:7]
	v_mfma_f32_16x16x32_bf16 v[0:3], v[180:183], v[212:215], v[0:3]
	s_setprio 0
	s_barrier
	s_add_i32 s59, s59, 2
	s_add_u32 s57, s57, 0x100
	s_addc_u32 s58, s58, 0
	s_cmpk_gt_u32 s59, 0xa9
	s_mov_b64 s[26:27], s[28:29]
	s_cbranch_scc0 .LBB0_1963
	s_and_b64 vcc, exec, s[22:23]
	s_cbranch_vccz .LBB0_1966
	s_barrier

	.amdhsa_kernel _Z10hybrid_fwd4Args
		.amdhsa_group_segment_fixed_size 0
		.amdhsa_private_segment_fixed_size 0
		.amdhsa_kernarg_size 416
		.amdhsa_user_sgpr_count 2
		.amdhsa_user_sgpr_dispatch_ptr 0
		.amdhsa_user_sgpr_queue_ptr 0
		.amdhsa_user_sgpr_kernarg_segment_ptr 1
		.amdhsa_user_sgpr_dispatch_id 0
		.amdhsa_user_sgpr_kernarg_preload_length 0
		.amdhsa_user_sgpr_kernarg_preload_offset 0
		.amdhsa_user_sgpr_private_segment_size 0
		.amdhsa_uses_dynamic_stack 0
		.amdhsa_enable_private_segment 0
		.amdhsa_system_sgpr_workgroup_id_x 1
		.amdhsa_system_sgpr_workgroup_id_y 0
		.amdhsa_system_sgpr_workgroup_id_z 0
		.amdhsa_system_sgpr_workgroup_info 0
		.amdhsa_system_vgpr_workitem_id 0
		.amdhsa_next_free_vgpr 256
		.amdhsa_next_free_sgpr 102
		.amdhsa_accum_offset 256
		.amdhsa_reserve_vcc 1
		.amdhsa_float_round_mode_32 0
		.amdhsa_float_round_mode_16_64 0
		.amdhsa_float_denorm_mode_32 3
		.amdhsa_float_denorm_mode_16_64 3
		.amdhsa_dx10_clamp 1
		.amdhsa_ieee_mode 1
		.amdhsa_fp16_overflow 0
		.amdhsa_tg_split 0
		.amdhsa_exception_fp_ieee_invalid_op 0
		.amdhsa_exception_fp_denorm_src 0
		.amdhsa_exception_fp_ieee_div_zero 0
		.amdhsa_exception_fp_ieee_overflow 0
		.amdhsa_exception_fp_ieee_underflow 0
		.amdhsa_exception_fp_ieee_inexact 0
		.amdhsa_exception_int_div_zero 0
	.end_amdhsa_kernel

amdhsa.kernels:
  - .agpr_count:     0
    .args:
      - .offset:         0
        .size:           160
        .value_kind:     by_value
      - .offset:         160
        .size:           4
        .value_kind:     hidden_block_count_x
      - .offset:         164
        .size:           4
        .value_kind:     hidden_block_count_y
      - .offset:         168
        .size:           4
        .value_kind:     hidden_block_count_z
      - .offset:         172
        .size:           2
        .value_kind:     hidden_group_size_x
      - .offset:         174
        .size:           2
        .value_kind:     hidden_group_size_y
      - .offset:         176
        .size:           2
        .value_kind:     hidden_group_size_z
      - .offset:         178
        .size:           2
        .value_kind:     hidden_remainder_x
      - .offset:         180
        .size:           2
        .value_kind:     hidden_remainder_y
      - .offset:         182
        .size:           2
        .value_kind:     hidden_remainder_z
      - .offset:         200
        .size:           8
        .value_kind:     hidden_global_offset_x
      - .offset:         208
        .size:           8
        .value_kind:     hidden_global_offset_y
      - .offset:         216
        .size:           8
        .value_kind:     hidden_global_offset_z
      - .offset:         224
        .size:           2
        .value_kind:     hidden_grid_dims
      - .offset:         280
        .size:           4
        .value_kind:     hidden_dynamic_lds_size
    .group_segment_fixed_size: 0
    .kernarg_segment_align: 8
    .kernarg_segment_size: 416
    .language:       OpenCL C
    .language_version:
      - 2
      - 0
    .max_flat_workgroup_size: 512
    .name:           _Z10hybrid_fwd4Args
    .private_segment_fixed_size: 0
    .sgpr_count:     108
    .sgpr_spill_count: 112
    .symbol:         _Z10hybrid_fwd4Args.kd
    .uniform_work_group_size: 1
    .uses_dynamic_stack: false
    .vgpr_count:     256
    .vgpr_spill_count: 0
    .wavefront_size: 64
